# P0 adaLN item: the wave's 32 weight rows are touched (L2 warm) before the silu staging so the GEMV loop's serial loads hit L2; on top of previous
# baseline (speedup 1.0000x reference)
; __device__ __forceinline__ void phase0(const Args& a, LAS unsigned char* L) {
;     ...
;             const int kk = tid & 255, rh = tid >> 8;
;             float cp[8], cs[16];
;             const float* p0 = a.in[2] + (size_t)rh * DM + kq * 256 + kk; const float* p1 = a.in[3] + (size_t)rh * DM + kq * 256 + kk;
; #pragma unroll
;             for (int n = 0; n < 8; ++n) cp[n] = p0[(size_t)(2 * n) * DM];
; #pragma unroll
;             for (int n = 0; n < 16; ++n) cs[n] = p1[(size_t)(2 * n) * DM];
;     ...
;         const float* wp = a.in[8] + (size_t)(kq * 256 + wave * 32) * 3072 + cc * 64 + lane;
; #pragma unroll 16
;         for (int i = 0; i < 32; ++i) {
;             const float w = wp[(size_t)i * 3072];
.LBB0_8:
	s_and_b32 s97, s96, 3
	s_lshl_b32 s98, s97, 8
	s_add_i32 s98, s98, s77
	s_mul_hi_i32 s99, s98, 0x3000
	s_mul_i32 s98, s98, 0x3000
	s_add_u32 s98, s52, s98
	s_addc_u32 s99, s53, s99
	s_lshr_b32 s100, s96, 2
	s_lshl_b32 s100, s100, 8
	s_add_u32 s98, s98, s100
	s_addc_u32 s99, s99, 0
	global_load_dword v200, v10, s[98:99]
	s_add_u32 s98, s98, 0x3000
	s_addc_u32 s99, s99, 0
	global_load_dword v200, v10, s[98:99]
	s_add_u32 s98, s98, 0x3000
	s_addc_u32 s99, s99, 0
	global_load_dword v200, v10, s[98:99]
	s_add_u32 s98, s98, 0x3000
	s_addc_u32 s99, s99, 0
	global_load_dword v200, v10, s[98:99]
	s_add_u32 s98, s98, 0x3000
	s_addc_u32 s99, s99, 0
	global_load_dword v200, v10, s[98:99]
	s_add_u32 s98, s98, 0x3000
	s_addc_u32 s99, s99, 0
	global_load_dword v200, v10, s[98:99]
	s_add_u32 s98, s98, 0x3000
	s_addc_u32 s99, s99, 0
	global_load_dword v200, v10, s[98:99]
	s_add_u32 s98, s98, 0x3000
	s_addc_u32 s99, s99, 0
	global_load_dword v200, v10, s[98:99]
	s_add_u32 s98, s98, 0x3000
	s_addc_u32 s99, s99, 0
	global_load_dword v200, v10, s[98:99]
	s_add_u32 s98, s98, 0x3000
	s_addc_u32 s99, s99, 0
	global_load_dword v200, v10, s[98:99]
	s_add_u32 s98, s98, 0x3000
	s_addc_u32 s99, s99, 0
	global_load_dword v200, v10, s[98:99]
	s_add_u32 s98, s98, 0x3000
	s_addc_u32 s99, s99, 0
	global_load_dword v200, v10, s[98:99]
	s_add_u32 s98, s98, 0x3000
	s_addc_u32 s99, s99, 0
	global_load_dword v200, v10, s[98:99]
	s_add_u32 s98, s98, 0x3000
	s_addc_u32 s99, s99, 0
	global_load_dword v200, v10, s[98:99]
	s_add_u32 s98, s98, 0x3000
	s_addc_u32 s99, s99, 0
	global_load_dword v200, v10, s[98:99]
	s_add_u32 s98, s98, 0x3000
	s_addc_u32 s99, s99, 0
	global_load_dword v200, v10, s[98:99]
	s_add_u32 s98, s98, 0x3000
	s_addc_u32 s99, s99, 0
	global_load_dword v200, v10, s[98:99]
	s_add_u32 s98, s98, 0x3000
	s_addc_u32 s99, s99, 0
	global_load_dword v200, v10, s[98:99]
	s_add_u32 s98, s98, 0x3000
	s_addc_u32 s99, s99, 0
	global_load_dword v200, v10, s[98:99]
	s_add_u32 s98, s98, 0x3000
	s_addc_u32 s99, s99, 0
	global_load_dword v200, v10, s[98:99]
	s_add_u32 s98, s98, 0x3000
	s_addc_u32 s99, s99, 0
	global_load_dword v200, v10, s[98:99]
	s_add_u32 s98, s98, 0x3000
	s_addc_u32 s99, s99, 0
	global_load_dword v200, v10, s[98:99]
	s_add_u32 s98, s98, 0x3000
	s_addc_u32 s99, s99, 0
	global_load_dword v200, v10, s[98:99]
	s_add_u32 s98, s98, 0x3000
	s_addc_u32 s99, s99, 0
	global_load_dword v200, v10, s[98:99]
	s_add_u32 s98, s98, 0x3000
	s_addc_u32 s99, s99, 0
	global_load_dword v200, v10, s[98:99]
	s_add_u32 s98, s98, 0x3000
	s_addc_u32 s99, s99, 0
	global_load_dword v200, v10, s[98:99]
	s_add_u32 s98, s98, 0x3000
	s_addc_u32 s99, s99, 0
	global_load_dword v200, v10, s[98:99]
	s_add_u32 s98, s98, 0x3000
	s_addc_u32 s99, s99, 0
	global_load_dword v200, v10, s[98:99]
	s_add_u32 s98, s98, 0x3000
	s_addc_u32 s99, s99, 0
	global_load_dword v200, v10, s[98:99]
	s_add_u32 s98, s98, 0x3000
	s_addc_u32 s99, s99, 0
	global_load_dword v200, v10, s[98:99]
	s_add_u32 s98, s98, 0x3000
	s_addc_u32 s99, s99, 0
	global_load_dword v200, v10, s[98:99]
	s_add_u32 s98, s98, 0x3000
	s_addc_u32 s99, s99, 0
	global_load_dword v200, v10, s[98:99]
	s_lshl_b32 s14, s97, 10
	v_lshl_add_u64 v[2:3], v[14:15], 0, s[14:15]
	v_add_co_u32_e32 v4, vcc, 0x2000, v2
	s_lshl_b32 s16, s97, 8
	s_nop 0
	v_addc_co_u32_e32 v5, vcc, 0, v3, vcc
	v_add_co_u32_e32 v18, vcc, 0x4000, v2
	v_mov_b32_e32 v50, 0
	s_nop 0
	v_addc_co_u32_e32 v19, vcc, 0, v3, vcc
	v_add_co_u32_e32 v20, vcc, 0x6000, v2
	v_mov_b32_e32 v51, v11
	s_nop 0
	v_addc_co_u32_e32 v21, vcc, 0, v3, vcc
	v_add_co_u32_e32 v22, vcc, 0x8000, v2
	v_mov_b32_e32 v52, 0
	s_nop 0
	v_addc_co_u32_e32 v23, vcc, 0, v3, vcc
	v_add_co_u32_e32 v24, vcc, 0xa000, v2
	v_mov_b32_e32 v53, v11
	s_nop 0
	v_addc_co_u32_e32 v25, vcc, 0, v3, vcc
	v_add_co_u32_e32 v26, vcc, 0xc000, v2
	v_mov_b32_e32 v54, 0
	s_nop 0
	v_addc_co_u32_e32 v27, vcc, 0, v3, vcc
	v_add_co_u32_e32 v28, vcc, 0xe000, v2
	v_mov_b32_e32 v55, v11
	s_nop 0
	v_addc_co_u32_e32 v29, vcc, 0, v3, vcc
	global_load_dword v30, v[2:3], off
	global_load_dword v31, v[4:5], off
	global_load_dword v32, v[18:19], off
	global_load_dword v33, v[20:21], off
	global_load_dword v34, v[22:23], off
	global_load_dword v35, v[24:25], off
	global_load_dword v36, v[26:27], off
	global_load_dword v37, v[28:29], off
	v_lshl_add_u64 v[2:3], v[16:17], 0, s[14:15]
	v_add_co_u32_e32 v4, vcc, s79, v2
	s_add_i32 s14, s16, s77
	s_nop 0
	v_addc_co_u32_e32 v5, vcc, 0, v3, vcc
	v_add_co_u32_e32 v18, vcc, s80, v2
	s_mul_hi_i32 s16, s14, 0x3000
	s_nop 0
	v_addc_co_u32_e32 v19, vcc, 0, v3, vcc
	v_add_co_u32_e32 v20, vcc, s81, v2
	s_mulk_i32 s14, 0x3000
	s_nop 0
	v_addc_co_u32_e32 v21, vcc, 0, v3, vcc
	v_add_co_u32_e32 v22, vcc, s82, v2
	s_add_u32 s14, s52, s14
	s_nop 0
	v_addc_co_u32_e32 v23, vcc, 0, v3, vcc
	v_add_co_u32_e32 v24, vcc, s83, v2
	s_addc_u32 s33, s53, s16
	s_nop 0
	v_addc_co_u32_e32 v25, vcc, 0, v3, vcc
	v_add_co_u32_e32 v26, vcc, s84, v2
	s_lshl_b32 s16, s96, 4
	s_nop 0
	v_addc_co_u32_e32 v27, vcc, 0, v3, vcc
	v_add_co_u32_e32 v28, vcc, s85, v2
	s_and_b32 s34, s16, 0xffffffc0
	s_nop 0
	v_addc_co_u32_e32 v29, vcc, 0, v3, vcc
	global_load_dword v38, v[2:3], off
	global_load_dword v39, v[4:5], off
	global_load_dword v40, v[18:19], off
	global_load_dword v41, v[20:21], off
	global_load_dword v42, v[22:23], off
	global_load_dword v43, v[24:25], off
	global_load_dword v44, v[26:27], off
	global_load_dword v45, v[28:29], off
	v_add_co_u32_e32 v4, vcc, s86, v2
	s_ashr_i32 s35, s34, 31
	s_nop 0
	v_addc_co_u32_e32 v5, vcc, 0, v3, vcc
	v_add_co_u32_e32 v18, vcc, s87, v2
	s_lshl_b64 s[16:17], s[34:35], 2
	s_nop 0
	v_addc_co_u32_e32 v19, vcc, 0, v3, vcc
	v_add_co_u32_e32 v20, vcc, s88, v2
	s_add_u32 s16, s14, s16
	s_nop 0
	v_addc_co_u32_e32 v21, vcc, 0, v3, vcc
	v_add_co_u32_e32 v22, vcc, s89, v2
	s_addc_u32 s17, s33, s17
	s_nop 0
	v_addc_co_u32_e32 v23, vcc, 0, v3, vcc
	v_add_co_u32_e32 v24, vcc, s90, v2
	s_mov_b32 s33, s15
	s_nop 0
	v_addc_co_u32_e32 v25, vcc, 0, v3, vcc
	v_add_co_u32_e32 v26, vcc, s91, v2
	v_mov_b32_e32 v56, 0
	s_nop 0
	v_addc_co_u32_e32 v27, vcc, 0, v3, vcc
	v_add_co_u32_e32 v28, vcc, s92, v2
	v_mov_b32_e32 v57, v11
	s_nop 0
	v_addc_co_u32_e32 v29, vcc, 0, v3, vcc
	v_add_co_u32_e32 v2, vcc, s93, v2
	s_waitcnt vmcnt(15)
; __device__ __forceinline__ float sigmoidf_(float x) { return __builtin_amdgcn_rcpf(1.f + __builtin_amdgcn_exp2f(x * -1.44269504f)); }
; __device__ __forceinline__ void phase0(const Args& a, LAS unsigned char* L) {
;     ...
;             for (int n = 0; n < 8; ++n) sC[kk * 48 + rh + 2 * n] = cp[n] * sigmoidf_(cp[n]);
; #pragma unroll
;             for (int n = 0; n < 16; ++n) sC[kk * 48 + 16 + rh + 2 * n] = cs[n] * sigmoidf_(cs[n]);
;         }
;         __syncthreads();
;         float acc[48];
; #pragma unroll
;         for (int r = 0; r < 48; ++r) acc[r] = 0.f;
	v_mul_f32_e32 v46, 0xbfb8aa3b, v30
	v_addc_co_u32_e32 v3, vcc, 0, v3, vcc
	global_load_dword v4, v[4:5], off
	s_nop 0
	global_load_dword v5, v[18:19], off
	s_nop 0
	global_load_dword v18, v[20:21], off
	global_load_dword v19, v[22:23], off
	s_nop 0
	global_load_dword v20, v[24:25], off
	global_load_dword v21, v[26:27], off
	global_load_dword v22, v[28:29], off
	s_nop 0
	global_load_dword v2, v[2:3], off
	s_waitcnt vmcnt(22)
	v_mul_f32_e32 v47, 0xbfb8aa3b, v31
	v_exp_f32_e32 v46, v46
	v_exp_f32_e32 v47, v47
	s_waitcnt vmcnt(21)
	v_mul_f32_e32 v24, 0xbfb8aa3b, v32
	v_exp_f32_e32 v24, v24
	v_add_f32_e32 v3, 1.0, v46
	v_add_f32_e32 v23, 1.0, v47
	v_rcp_f32_e32 v3, v3
	v_rcp_f32_e32 v23, v23
	s_waitcnt vmcnt(18)
	v_mul_f32_e32 v25, 0xbfb8aa3b, v35
	v_exp_f32_e32 v25, v25
	v_mul_f32_e32 v3, v30, v3
	v_mul_f32_e32 v23, v31, v23
	ds_write2_b32 v1, v3, v23 offset1:2
	v_mul_f32_e32 v23, 0xbfb8aa3b, v33
	v_add_f32_e32 v3, 1.0, v24
	v_exp_f32_e32 v23, v23
	v_mul_f32_e32 v24, 0xbfb8aa3b, v34
	v_exp_f32_e32 v24, v24
	v_rcp_f32_e32 v3, v3
	v_add_f32_e32 v23, 1.0, v23
	v_rcp_f32_e32 v23, v23
	v_add_f32_e32 v24, 1.0, v24
	v_rcp_f32_e32 v24, v24
	v_mul_f32_e32 v3, v32, v3
	v_mul_f32_e32 v23, v33, v23
	ds_write2_b32 v1, v3, v23 offset0:4 offset1:6
	v_mul_f32_e32 v3, v34, v24
	v_add_f32_e32 v23, 1.0, v25
	s_waitcnt vmcnt(17)
	v_mul_f32_e32 v24, 0xbfb8aa3b, v36
	s_waitcnt vmcnt(16)
	v_mul_f32_e32 v25, 0xbfb8aa3b, v37
	v_exp_f32_e32 v24, v24
	v_exp_f32_e32 v25, v25
	v_rcp_f32_e32 v23, v23
	v_mov_b32_e32 v58, 0
	v_add_f32_e32 v24, 1.0, v24
	v_add_f32_e32 v25, 1.0, v25
	v_rcp_f32_e32 v24, v24
	v_rcp_f32_e32 v25, v25
	v_mul_f32_e32 v23, v35, v23
	ds_write2_b32 v1, v3, v23 offset0:8 offset1:10
	v_mul_f32_e32 v3, v36, v24
	v_mul_f32_e32 v23, v37, v25
	s_waitcnt vmcnt(15)
	v_mul_f32_e32 v24, 0xbfb8aa3b, v38
	s_waitcnt vmcnt(14)
	v_mul_f32_e32 v25, 0xbfb8aa3b, v39
	v_exp_f32_e32 v24, v24
	v_exp_f32_e32 v25, v25
	ds_write2_b32 v1, v3, v23 offset0:12 offset1:14
	v_mov_b32_e32 v59, v11
	v_add_f32_e32 v3, 1.0, v24
	v_add_f32_e32 v23, 1.0, v25
	v_rcp_f32_e32 v3, v3
	v_rcp_f32_e32 v23, v23
	s_waitcnt vmcnt(13)
	v_mul_f32_e32 v24, 0xbfb8aa3b, v40
	v_exp_f32_e32 v24, v24
	v_mul_f32_e32 v3, v38, v3
	v_mul_f32_e32 v23, v39, v23
	ds_write2_b32 v1, v3, v23 offset0:16 offset1:18
	s_waitcnt vmcnt(12)
	v_mul_f32_e32 v23, 0xbfb8aa3b, v41
	v_add_f32_e32 v3, 1.0, v24
	v_exp_f32_e32 v23, v23
	s_waitcnt vmcnt(11)
	v_mul_f32_e32 v24, 0xbfb8aa3b, v42
	v_exp_f32_e32 v24, v24
	v_rcp_f32_e32 v3, v3
	v_add_f32_e32 v23, 1.0, v23
	v_rcp_f32_e32 v23, v23
	v_add_f32_e32 v24, 1.0, v24
	s_waitcnt vmcnt(10)
	v_mul_f32_e32 v25, 0xbfb8aa3b, v43
	v_rcp_f32_e32 v24, v24
	v_exp_f32_e32 v25, v25
	v_mul_f32_e32 v3, v40, v3
	v_mul_f32_e32 v23, v41, v23
	ds_write2_b32 v1, v3, v23 offset0:20 offset1:22
	v_mul_f32_e32 v3, v42, v24
	v_add_f32_e32 v23, 1.0, v25
	s_waitcnt vmcnt(9)
	v_mul_f32_e32 v24, 0xbfb8aa3b, v44
	s_waitcnt vmcnt(8)
	v_mul_f32_e32 v25, 0xbfb8aa3b, v45
	v_exp_f32_e32 v24, v24
	v_exp_f32_e32 v25, v25
	v_rcp_f32_e32 v23, v23
	v_mov_b32_e32 v60, 0
	v_add_f32_e32 v24, 1.0, v24
	v_add_f32_e32 v25, 1.0, v25
	v_rcp_f32_e32 v24, v24
	v_rcp_f32_e32 v25, v25
	v_mul_f32_e32 v23, v43, v23
	ds_write2_b32 v1, v3, v23 offset0:24 offset1:26
	v_mul_f32_e32 v3, v44, v24
	v_mul_f32_e32 v23, v45, v25
	s_waitcnt vmcnt(7)
	v_mul_f32_e32 v24, 0xbfb8aa3b, v4
	s_waitcnt vmcnt(6)
	v_mul_f32_e32 v25, 0xbfb8aa3b, v5
	v_exp_f32_e32 v24, v24
	v_exp_f32_e32 v25, v25
	ds_write2_b32 v1, v3, v23 offset0:28 offset1:30
	v_mov_b32_e32 v61, v11
	v_add_f32_e32 v3, 1.0, v24
	v_add_f32_e32 v23, 1.0, v25
	v_rcp_f32_e32 v3, v3
	v_rcp_f32_e32 v23, v23
	s_waitcnt vmcnt(5)
	v_mul_f32_e32 v24, 0xbfb8aa3b, v18
	v_exp_f32_e32 v24, v24
	v_mul_f32_e32 v3, v4, v3
	v_mul_f32_e32 v4, v5, v23
	ds_write2_b32 v1, v3, v4 offset0:32 offset1:34
	s_waitcnt vmcnt(4)
	v_mul_f32_e32 v4, 0xbfb8aa3b, v19
	v_add_f32_e32 v3, 1.0, v24
	v_exp_f32_e32 v4, v4
	s_waitcnt vmcnt(3)
	v_mul_f32_e32 v5, 0xbfb8aa3b, v20
	v_rcp_f32_e32 v3, v3
	v_exp_f32_e32 v5, v5
	v_add_f32_e32 v4, 1.0, v4
	v_rcp_f32_e32 v4, v4
	v_mul_f32_e32 v3, v18, v3
	v_add_f32_e32 v5, 1.0, v5
	s_waitcnt vmcnt(2)
	v_mul_f32_e32 v18, 0xbfb8aa3b, v21
	v_rcp_f32_e32 v5, v5
	v_exp_f32_e32 v18, v18
	v_mul_f32_e32 v4, v19, v4
	ds_write2_b32 v1, v3, v4 offset0:36 offset1:38
	v_mul_f32_e32 v3, v20, v5
	v_add_f32_e32 v4, 1.0, v18
	s_waitcnt vmcnt(1)
	v_mul_f32_e32 v5, 0xbfb8aa3b, v22
	s_waitcnt vmcnt(0)
	v_mul_f32_e32 v18, 0xbfb8aa3b, v2
	v_exp_f32_e32 v5, v5
	v_exp_f32_e32 v18, v18
	v_rcp_f32_e32 v4, v4
	v_mov_b32_e32 v20, 0
	v_add_f32_e32 v5, 1.0, v5
	v_add_f32_e32 v18, 1.0, v18
	v_rcp_f32_e32 v5, v5
	v_rcp_f32_e32 v18, v18
	v_mul_f32_e32 v4, v21, v4
	ds_write2_b32 v1, v3, v4 offset0:40 offset1:42
	v_mul_f32_e32 v3, v22, v5
	v_mul_f32_e32 v2, v2, v18
	ds_write2_b32 v1, v3, v2 offset0:44 offset1:46
	v_lshl_add_u64 v[18:19], s[16:17], 0, v[10:11]
	v_mov_b32_e32 v21, v11
	v_mov_b32_e32 v62, 0
	v_mov_b32_e32 v63, v11
	v_mov_b32_e32 v2, 0
	v_mov_b32_e32 v3, v11
	v_mov_b32_e32 v22, 0
	v_mov_b32_e32 v23, v11
	v_mov_b32_e32 v4, 0
	v_mov_b32_e32 v5, v11
	v_mov_b32_e32 v26, 0
	v_mov_b32_e32 v27, v11
	v_mov_b32_e32 v24, 0
	v_mov_b32_e32 v25, v11
	v_mov_b32_e32 v30, 0
	v_mov_b32_e32 v31, v11
	v_mov_b32_e32 v28, 0
	v_mov_b32_e32 v29, v11
	v_mov_b32_e32 v34, 0
	v_mov_b32_e32 v35, v11
	v_mov_b32_e32 v32, 0
	v_mov_b32_e32 v33, v11
	v_mov_b32_e32 v38, 0
	v_mov_b32_e32 v39, v11
	v_mov_b32_e32 v36, 0
	v_mov_b32_e32 v37, v11
	v_mov_b32_e32 v42, 0
	v_mov_b32_e32 v43, v11
	v_mov_b32_e32 v40, 0
	v_mov_b32_e32 v41, v11
	v_mov_b32_e32 v46, 0
	v_mov_b32_e32 v47, v11
	v_mov_b32_e32 v44, 0
	v_mov_b32_e32 v45, v11
	v_mov_b32_e32 v48, 0
	v_mov_b32_e32 v49, v11
	s_waitcnt lgkmcnt(0)
	s_barrier
